# layer-0 context Fourier tiles assigned to workgroups 16..31 so they no longer stack on the 16 workgroups that also carry a context attention item
# speedup vs baseline: 1.0037x; 1.0034x over previous
.LBB0_449:
	s_or_b64 exec, exec, s[12:13]
	v_readlane_b32 s0, v205, 9
	v_readlane_b32 s1, v205, 10
	s_and_b64 s[0:1], s[0:1], exec
	s_cselect_b32 s2, s75, 0x200
	v_mov_b32_e32 v33, v138
	s_cmp_ge_i32 s96, s2
	s_mov_b32 s57, 0xfffffc0
	s_mov_b32 s49, 0x3200000
	s_cbranch_scc1 .LBB0_459
	v_lshlrev_b32_e32 v0, 3, v33
	v_and_b32_e32 v32, 0x78, v0
	v_lshlrev_b32_e32 v34, 2, v32
	s_add_i32 s3, s96, 0x1f0
	s_and_b32 s3, s3, 0x1ff
	s_branch .LBB0_452
